# P4 attention: exp/convert of each 16-key P group interleaved with the PV MFMAs of the previous group
# speedup vs baseline: 1.0256x; 1.0093x over previous
.LBB0_2517:
	v_mul_f32_e32 v12, 0xbe16c740, v11
	v_fmamk_f32 v64, v64, 0x3e16c740, v12
	v_fmamk_f32 v65, v65, 0x3e16c740, v12
	v_fmamk_f32 v66, v66, 0x3e16c740, v12
	v_fmamk_f32 v67, v67, 0x3e16c740, v12
	v_fmamk_f32 v68, v68, 0x3e16c740, v12
	v_fmamk_f32 v69, v69, 0x3e16c740, v12
	v_fmamk_f32 v70, v70, 0x3e16c740, v12
	v_fmamk_f32 v71, v71, 0x3e16c740, v12
	v_exp_f32_e32 v64, v64
	v_exp_f32_e32 v65, v65
	v_exp_f32_e32 v66, v66
	v_exp_f32_e32 v67, v67
	v_exp_f32_e32 v68, v68
	v_exp_f32_e32 v69, v69
	v_exp_f32_e32 v70, v70
	v_exp_f32_e32 v71, v71
	v_cvt_pk_bf16_f32 v64, v64, v65
	v_cvt_pk_bf16_f32 v65, v66, v67
	v_cvt_pk_bf16_f32 v66, v68, v69
	v_cvt_pk_bf16_f32 v67, v70, v71
	s_setprio 1
	s_waitcnt lgkmcnt(0)
	v_mfma_f32_32x32x16_bf16 v[32:47], v[226:229], v[64:67], v[32:47]
	v_fmamk_f32 v72, v72, 0x3e16c740, v12
	v_fmamk_f32 v73, v73, 0x3e16c740, v12
	v_fmamk_f32 v74, v74, 0x3e16c740, v12
	v_fmamk_f32 v75, v75, 0x3e16c740, v12
	v_fmamk_f32 v76, v76, 0x3e16c740, v12
	v_fmamk_f32 v77, v77, 0x3e16c740, v12
	v_fmamk_f32 v78, v78, 0x3e16c740, v12
	v_mfma_f32_32x32x16_bf16 v[16:31], v[230:233], v[64:67], v[16:31]
	v_fmamk_f32 v79, v79, 0x3e16c740, v12
	v_exp_f32_e32 v72, v72
	v_exp_f32_e32 v73, v73
	v_exp_f32_e32 v74, v74
	v_exp_f32_e32 v75, v75
	v_exp_f32_e32 v76, v76
	v_exp_f32_e32 v77, v77
	v_mfma_f32_32x32x16_bf16 v[48:63], v[250:253], v[64:67], v[48:63]
	v_exp_f32_e32 v78, v78
	v_exp_f32_e32 v79, v79
	v_cvt_pk_bf16_f32 v72, v72, v73
	v_cvt_pk_bf16_f32 v73, v74, v75
	v_cvt_pk_bf16_f32 v74, v76, v77
	v_cvt_pk_bf16_f32 v75, v78, v79
	s_nop 1
	v_mfma_f32_32x32x16_bf16 v[32:47], v[234:237], v[72:75], v[32:47]
	v_fmamk_f32 v80, v80, 0x3e16c740, v12
	v_fmamk_f32 v81, v81, 0x3e16c740, v12
	v_fmamk_f32 v82, v82, 0x3e16c740, v12
	v_fmamk_f32 v83, v83, 0x3e16c740, v12
	v_fmamk_f32 v84, v84, 0x3e16c740, v12
	v_fmamk_f32 v85, v85, 0x3e16c740, v12
	v_fmamk_f32 v86, v86, 0x3e16c740, v12
	v_mfma_f32_32x32x16_bf16 v[16:31], v[238:241], v[72:75], v[16:31]
	v_fmamk_f32 v87, v87, 0x3e16c740, v12
	v_exp_f32_e32 v80, v80
	v_exp_f32_e32 v81, v81
	v_exp_f32_e32 v82, v82
	v_exp_f32_e32 v83, v83
	v_exp_f32_e32 v84, v84
	v_exp_f32_e32 v85, v85
	v_mfma_f32_32x32x16_bf16 v[48:63], v[250:253], v[72:75], v[48:63]
	v_exp_f32_e32 v86, v86
	v_exp_f32_e32 v87, v87
	v_cvt_pk_bf16_f32 v80, v80, v81
	v_cvt_pk_bf16_f32 v81, v82, v83
	v_cvt_pk_bf16_f32 v82, v84, v85
	v_cvt_pk_bf16_f32 v83, v86, v87
	s_nop 1
	v_mfma_f32_32x32x16_bf16 v[32:47], v[242:245], v[80:83], v[32:47]
	v_fmamk_f32 v88, v88, 0x3e16c740, v12
	v_fmamk_f32 v89, v89, 0x3e16c740, v12
	v_fmamk_f32 v90, v90, 0x3e16c740, v12
	v_fmamk_f32 v91, v91, 0x3e16c740, v12
	v_fmamk_f32 v92, v92, 0x3e16c740, v12
	v_fmamk_f32 v93, v93, 0x3e16c740, v12
	v_fmamk_f32 v94, v94, 0x3e16c740, v12
	v_mfma_f32_32x32x16_bf16 v[16:31], v[246:249], v[80:83], v[16:31]
	v_fmamk_f32 v95, v95, 0x3e16c740, v12
	v_exp_f32_e32 v88, v88
	v_exp_f32_e32 v89, v89
	v_exp_f32_e32 v90, v90
	v_exp_f32_e32 v91, v91
	v_exp_f32_e32 v92, v92
	v_exp_f32_e32 v93, v93
	v_mfma_f32_32x32x16_bf16 v[48:63], v[250:253], v[80:83], v[48:63]
	v_exp_f32_e32 v94, v94
	v_exp_f32_e32 v95, v95
	v_cvt_pk_bf16_f32 v88, v88, v89
	v_cvt_pk_bf16_f32 v89, v90, v91
	v_cvt_pk_bf16_f32 v90, v92, v93
	v_cvt_pk_bf16_f32 v91, v94, v95
	s_nop 1
	v_mfma_f32_32x32x16_bf16 v[32:47], v[214:217], v[88:91], v[32:47]
	v_mfma_f32_32x32x16_bf16 v[16:31], v[218:221], v[88:91], v[16:31]
	v_mfma_f32_32x32x16_bf16 v[48:63], v[250:253], v[88:91], v[48:63]
	s_setprio 0
	s_addk_i32 s86, 0x5000
	s_add_i32 s87, s87, 2
	s_cmpk_eq_u32 s86, 0xa000
	s_cbranch_scc1 .LBB0_2519

.LBB0_2558:
	v_mul_f32_e32 v80, 0xbe38aa3b, v50
	v_fmamk_f32 v171, v171, 0x3e38aa3b, v80
	v_fmamk_f32 v172, v172, 0x3e38aa3b, v80
	v_fmamk_f32 v173, v173, 0x3e38aa3b, v80
	v_fmamk_f32 v68, v68, 0x3e38aa3b, v80
	v_fmamk_f32 v69, v69, 0x3e38aa3b, v80
	v_fmamk_f32 v70, v70, 0x3e38aa3b, v80
	v_fmamk_f32 v71, v71, 0x3e38aa3b, v80
	v_fmamk_f32 v72, v72, 0x3e38aa3b, v80
	v_exp_f32_e32 v171, v171
	v_exp_f32_e32 v172, v172
	v_exp_f32_e32 v173, v173
	v_exp_f32_e32 v68, v68
	v_exp_f32_e32 v69, v69
	v_exp_f32_e32 v70, v70
	v_exp_f32_e32 v71, v71
	v_exp_f32_e32 v72, v72
	v_cvt_pk_bf16_f32 v250, v171, v172
	v_cvt_pk_bf16_f32 v251, v173, v68
	v_cvt_pk_bf16_f32 v252, v69, v70
	v_cvt_pk_bf16_f32 v253, v71, v72
	s_setprio 1
	s_waitcnt lgkmcnt(0)
	v_mfma_f32_32x32x16_bf16 v[18:33], v[214:217], v[250:253], v[18:33]
	v_fmamk_f32 v73, v73, 0x3e38aa3b, v80
	v_fmamk_f32 v74, v74, 0x3e38aa3b, v80
	v_fmamk_f32 v75, v75, 0x3e38aa3b, v80
	v_fmamk_f32 v76, v76, 0x3e38aa3b, v80
	v_fmamk_f32 v77, v77, 0x3e38aa3b, v80
	v_fmamk_f32 v78, v78, 0x3e38aa3b, v80
	v_fmamk_f32 v79, v79, 0x3e38aa3b, v80
	v_mfma_f32_32x32x16_bf16 v[2:17], v[218:221], v[250:253], v[2:17]
	v_fmamk_f32 v65, v65, 0x3e38aa3b, v80
	v_exp_f32_e32 v73, v73
	v_exp_f32_e32 v74, v74
	v_exp_f32_e32 v75, v75
	v_exp_f32_e32 v76, v76
	v_exp_f32_e32 v77, v77
	v_exp_f32_e32 v78, v78
	v_mfma_f32_32x32x16_bf16 v[34:49], v[246:249], v[250:253], v[34:49]
	v_exp_f32_e32 v79, v79
	v_exp_f32_e32 v65, v65
	v_cvt_pk_bf16_f32 v178, v73, v74
	v_cvt_pk_bf16_f32 v179, v75, v76
	v_cvt_pk_bf16_f32 v180, v77, v78
	v_cvt_pk_bf16_f32 v181, v79, v65
	s_nop 1
	v_mfma_f32_32x32x16_bf16 v[18:33], v[222:225], v[178:181], v[18:33]
	v_fmamk_f32 v66, v66, 0x3e38aa3b, v80
	v_fmamk_f32 v67, v67, 0x3e38aa3b, v80
	v_fmamk_f32 v52, v52, 0x3e38aa3b, v80
	v_fmamk_f32 v53, v53, 0x3e38aa3b, v80
	v_fmamk_f32 v54, v54, 0x3e38aa3b, v80
	v_fmamk_f32 v55, v55, 0x3e38aa3b, v80
	v_fmamk_f32 v56, v56, 0x3e38aa3b, v80
	v_mfma_f32_32x32x16_bf16 v[2:17], v[226:229], v[178:181], v[2:17]
	v_fmamk_f32 v57, v57, 0x3e38aa3b, v80
	v_exp_f32_e32 v66, v66
	v_exp_f32_e32 v67, v67
	v_exp_f32_e32 v52, v52
	v_exp_f32_e32 v53, v53
	v_exp_f32_e32 v54, v54
	v_exp_f32_e32 v55, v55
	v_mfma_f32_32x32x16_bf16 v[34:49], v[246:249], v[178:181], v[34:49]
	v_exp_f32_e32 v56, v56
	v_exp_f32_e32 v57, v57
	v_cvt_pk_bf16_f32 v182, v66, v67
	v_cvt_pk_bf16_f32 v183, v52, v53
	v_cvt_pk_bf16_f32 v184, v54, v55
	v_cvt_pk_bf16_f32 v185, v56, v57
	s_nop 1
	v_mfma_f32_32x32x16_bf16 v[18:33], v[230:233], v[182:185], v[18:33]
	v_fmamk_f32 v58, v58, 0x3e38aa3b, v80
	v_fmamk_f32 v59, v59, 0x3e38aa3b, v80
	v_fmamk_f32 v60, v60, 0x3e38aa3b, v80
	v_fmamk_f32 v61, v61, 0x3e38aa3b, v80
	v_fmamk_f32 v62, v62, 0x3e38aa3b, v80
	v_fmamk_f32 v63, v63, 0x3e38aa3b, v80
	v_fmamk_f32 v64, v64, 0x3e38aa3b, v80
	v_mfma_f32_32x32x16_bf16 v[2:17], v[234:237], v[182:185], v[2:17]
	v_fmamk_f32 v51, v51, 0x3e38aa3b, v80
	v_exp_f32_e32 v58, v58
	v_exp_f32_e32 v59, v59
	v_exp_f32_e32 v60, v60
	v_exp_f32_e32 v61, v61
	v_exp_f32_e32 v62, v62
	v_exp_f32_e32 v63, v63
	v_mfma_f32_32x32x16_bf16 v[34:49], v[246:249], v[182:185], v[34:49]
	v_exp_f32_e32 v64, v64
	v_exp_f32_e32 v51, v51
	v_cvt_pk_bf16_f32 v186, v58, v59
	v_cvt_pk_bf16_f32 v187, v60, v61
	v_cvt_pk_bf16_f32 v188, v62, v63
	v_cvt_pk_bf16_f32 v189, v64, v51
	s_nop 1
	v_mfma_f32_32x32x16_bf16 v[18:33], v[238:241], v[186:189], v[18:33]
	v_mfma_f32_32x32x16_bf16 v[2:17], v[242:245], v[186:189], v[2:17]
	v_mfma_f32_32x32x16_bf16 v[34:49], v[246:249], v[186:189], v[34:49]
	s_setprio 0
	s_addk_i32 s71, 0x5000
	s_add_i32 s72, s72, 2
	s_cmpk_eq_u32 s71, 0xa000
	s_cbranch_scc1 .LBB0_2560
